# GEMM K-loops without the per-phase s_setprio flips (A/B: faster than with them on this megakernel)
# speedup vs baseline: 1.0322x; 1.0071x over previous
.LBB0_234:
	ds_read_b128 v[136:139], v167
	ds_read_b128 v[140:143], v167 offset:1024
	ds_read_b128 v[144:147], v167 offset:2048
	ds_read_b128 v[148:151], v167 offset:3072
	s_add_u32 s3, s10, 0xfff80080
	s_addc_u32 s28, s11, -1
	s_cmp_eq_u32 vcc_lo, 28
	s_cselect_b32 s35, s9, s28
	s_cselect_b32 s34, s89, s3
	s_cselect_b32 s29, s71, s95
	s_cselect_b32 s28, s91, s93
	v_lshl_add_u64 v[152:153], s[10:11], 0, v[132:133]
	s_add_i32 m0, s62, 0xc000
	ds_read_b128 v[172:175], v168
	ds_read_b128 v[190:193], v168 offset:1024
	ds_read_b128 v[194:197], v168 offset:2048
	ds_read_b128 v[198:201], v168 offset:3072
	ds_read_b128 v[202:205], v168 offset:4096
	ds_read_b128 v[206:209], v168 offset:5120
	ds_read_b128 v[224:227], v168 offset:6144
	ds_read_b128 v[228:231], v168 offset:7168
	global_load_lds_dwordx4 v[152:153], off
	v_lshl_add_u64 v[152:153], s[10:11], 0, v[134:135]
	s_add_i32 m0, s62, 0xe000
	s_nop 0
	global_load_lds_dwordx4 v[152:153], off
	s_waitcnt lgkmcnt(8)
	s_barrier
	s_waitcnt lgkmcnt(0)
	v_mfma_f32_16x16x32_bf16 v[124:127], v[136:139], v[172:175], v[124:127]
	v_mfma_f32_16x16x32_bf16 v[116:119], v[144:147], v[172:175], v[116:119]
	v_mfma_f32_16x16x32_bf16 v[108:111], v[136:139], v[194:197], v[108:111]
	v_mfma_f32_16x16x32_bf16 v[100:103], v[144:147], v[194:197], v[100:103]
	v_mfma_f32_16x16x32_bf16 v[92:95], v[136:139], v[202:205], v[92:95]
	v_mfma_f32_16x16x32_bf16 v[84:87], v[144:147], v[202:205], v[84:87]
	v_mfma_f32_16x16x32_bf16 v[76:79], v[136:139], v[224:227], v[76:79]
	v_mfma_f32_16x16x32_bf16 v[68:71], v[144:147], v[224:227], v[68:71]
	v_mfma_f32_16x16x32_bf16 v[124:127], v[140:143], v[190:193], v[124:127]
	v_mfma_f32_16x16x32_bf16 v[116:119], v[148:151], v[190:193], v[116:119]
	v_mfma_f32_16x16x32_bf16 v[108:111], v[140:143], v[198:201], v[108:111]
	v_mfma_f32_16x16x32_bf16 v[100:103], v[148:151], v[198:201], v[100:103]
	v_mfma_f32_16x16x32_bf16 v[92:95], v[140:143], v[206:209], v[92:95]
	v_mfma_f32_16x16x32_bf16 v[84:87], v[148:151], v[206:209], v[84:87]
	v_mfma_f32_16x16x32_bf16 v[76:79], v[140:143], v[228:231], v[76:79]
	v_mfma_f32_16x16x32_bf16 v[68:71], v[148:151], v[228:231], v[68:71]
	s_barrier
	s_add_i32 s3, s84, s61
	v_lshl_add_u64 v[152:153], s[28:29], 0, v[184:185]
	s_mov_b32 m0, s3
	ds_read_b128 v[232:235], v169
	ds_read_b128 v[236:239], v169 offset:1024
	ds_read_b128 v[240:243], v169 offset:2048
	ds_read_b128 v[244:247], v169 offset:3072
	global_load_lds_dwordx4 v[152:153], off
	v_lshl_add_u64 v[248:249], s[28:29], 0, v[188:189]
	s_add_i32 m0, s3, 0x2000
	s_nop 0
	global_load_lds_dwordx4 v[248:249], off
	s_barrier
	s_waitcnt lgkmcnt(0)
	v_mfma_f32_16x16x32_bf16 v[120:123], v[232:235], v[172:175], v[120:123]
	v_mfma_f32_16x16x32_bf16 v[112:115], v[240:243], v[172:175], v[112:115]
	v_mfma_f32_16x16x32_bf16 v[104:107], v[232:235], v[194:197], v[104:107]
	v_mfma_f32_16x16x32_bf16 v[96:99], v[240:243], v[194:197], v[96:99]
	v_mfma_f32_16x16x32_bf16 v[88:91], v[232:235], v[202:205], v[88:91]
	v_mfma_f32_16x16x32_bf16 v[80:83], v[240:243], v[202:205], v[80:83]
	v_mfma_f32_16x16x32_bf16 v[72:75], v[232:235], v[224:227], v[72:75]
	v_mfma_f32_16x16x32_bf16 v[64:67], v[240:243], v[224:227], v[64:67]
	v_mfma_f32_16x16x32_bf16 v[120:123], v[236:239], v[190:193], v[120:123]
	v_mfma_f32_16x16x32_bf16 v[112:115], v[244:247], v[190:193], v[112:115]
	v_mfma_f32_16x16x32_bf16 v[104:107], v[236:239], v[198:201], v[104:107]
	v_mfma_f32_16x16x32_bf16 v[96:99], v[244:247], v[198:201], v[96:99]
	v_mfma_f32_16x16x32_bf16 v[88:91], v[236:239], v[206:209], v[88:91]
	v_mfma_f32_16x16x32_bf16 v[80:83], v[244:247], v[206:209], v[80:83]
	v_mfma_f32_16x16x32_bf16 v[72:75], v[236:239], v[228:231], v[72:75]
	v_mfma_f32_16x16x32_bf16 v[64:67], v[244:247], v[228:231], v[64:67]
	s_mov_b32 m0, s62
	v_lshl_add_u64 v[250:251], s[34:35], 0, v[182:183]
	s_barrier
	ds_read_b128 v[172:175], v168 offset:16384
	ds_read_b128 v[190:193], v168 offset:17408
	ds_read_b128 v[194:197], v168 offset:18432
	ds_read_b128 v[198:201], v168 offset:19456
	ds_read_b128 v[202:205], v168 offset:20480
	ds_read_b128 v[206:209], v168 offset:21504
	ds_read_b128 v[224:227], v168 offset:22528
	ds_read_b128 v[228:231], v168 offset:23552
	global_load_lds_dwordx4 v[250:251], off
	v_lshl_add_u64 v[252:253], s[34:35], 0, v[186:187]
	s_mov_b32 m0, s63
	s_nop 0
	global_load_lds_dwordx4 v[252:253], off
	s_barrier
	s_waitcnt lgkmcnt(0)
	v_mfma_f32_16x16x32_bf16 v[60:63], v[136:139], v[172:175], v[60:63]
	v_mfma_f32_16x16x32_bf16 v[52:55], v[144:147], v[172:175], v[52:55]
	v_mfma_f32_16x16x32_bf16 v[44:47], v[136:139], v[194:197], v[44:47]
	v_mfma_f32_16x16x32_bf16 v[36:39], v[144:147], v[194:197], v[36:39]
	v_mfma_f32_16x16x32_bf16 v[28:31], v[136:139], v[202:205], v[28:31]
	v_mfma_f32_16x16x32_bf16 v[20:23], v[144:147], v[202:205], v[20:23]
	v_mfma_f32_16x16x32_bf16 v[12:15], v[136:139], v[224:227], v[12:15]
	v_mfma_f32_16x16x32_bf16 v[4:7], v[144:147], v[224:227], v[4:7]
	v_mfma_f32_16x16x32_bf16 v[60:63], v[140:143], v[190:193], v[60:63]
	v_mfma_f32_16x16x32_bf16 v[52:55], v[148:151], v[190:193], v[52:55]
	v_mfma_f32_16x16x32_bf16 v[44:47], v[140:143], v[198:201], v[44:47]
	v_mfma_f32_16x16x32_bf16 v[36:39], v[148:151], v[198:201], v[36:39]
	v_mfma_f32_16x16x32_bf16 v[28:31], v[140:143], v[206:209], v[28:31]
	v_mfma_f32_16x16x32_bf16 v[20:23], v[148:151], v[206:209], v[20:23]
	v_mfma_f32_16x16x32_bf16 v[12:15], v[140:143], v[228:231], v[12:15]
	v_mfma_f32_16x16x32_bf16 v[4:7], v[148:151], v[228:231], v[4:7]
	s_barrier
	s_add_u32 s74, s28, 0x80000
	s_addc_u32 s75, s29, 0
	s_add_i32 s3, s85, s61
	v_lshl_add_u64 v[136:137], s[74:75], 0, v[184:185]
	s_mov_b32 m0, s3
	s_nop 0
	global_load_lds_dwordx4 v[136:137], off
	v_lshl_add_u64 v[136:137], s[74:75], 0, v[188:189]
	s_add_i32 m0, s3, 0x2000
	s_nop 0
	global_load_lds_dwordx4 v[136:137], off
	s_waitcnt vmcnt(6)
	s_barrier
	v_mfma_f32_16x16x32_bf16 v[56:59], v[232:235], v[172:175], v[56:59]
	v_mfma_f32_16x16x32_bf16 v[48:51], v[240:243], v[172:175], v[48:51]
	v_mfma_f32_16x16x32_bf16 v[40:43], v[232:235], v[194:197], v[40:43]
	v_mfma_f32_16x16x32_bf16 v[32:35], v[240:243], v[194:197], v[32:35]
	v_mfma_f32_16x16x32_bf16 v[24:27], v[232:235], v[202:205], v[24:27]
	v_mfma_f32_16x16x32_bf16 v[16:19], v[240:243], v[202:205], v[16:19]
	v_mfma_f32_16x16x32_bf16 v[8:11], v[232:235], v[224:227], v[8:11]
	v_mfma_f32_16x16x32_bf16 v[0:3], v[240:243], v[224:227], v[0:3]
	v_mfma_f32_16x16x32_bf16 v[56:59], v[236:239], v[190:193], v[56:59]
	v_mfma_f32_16x16x32_bf16 v[48:51], v[244:247], v[190:193], v[48:51]
	v_mfma_f32_16x16x32_bf16 v[40:43], v[236:239], v[198:201], v[40:43]
	v_mfma_f32_16x16x32_bf16 v[32:35], v[244:247], v[198:201], v[32:35]
	v_mfma_f32_16x16x32_bf16 v[24:27], v[236:239], v[206:209], v[24:27]
	v_mfma_f32_16x16x32_bf16 v[16:19], v[244:247], v[206:209], v[16:19]
	v_mfma_f32_16x16x32_bf16 v[8:11], v[236:239], v[228:231], v[8:11]
	v_mfma_f32_16x16x32_bf16 v[0:3], v[244:247], v[228:231], v[0:3]
	s_add_i32 s3, 0, 0x18000
	v_add_u32_e32 v130, s3, v165
	s_barrier
	ds_read_b128 v[136:139], v130
	ds_read_b128 v[140:143], v130 offset:1024
	ds_read_b128 v[144:147], v130 offset:2048
	ds_read_b128 v[148:151], v130 offset:3072
	s_add_u32 s34, s34, 0x80000
	s_addc_u32 s35, s35, 0
	s_mov_b32 m0, s64
	v_lshl_add_u64 v[232:233], s[34:35], 0, v[182:183]
	ds_read_b128 v[172:175], v168 offset:32768
	ds_read_b128 v[190:193], v168 offset:33792
	ds_read_b128 v[194:197], v168 offset:34816
	ds_read_b128 v[198:201], v168 offset:35840
	ds_read_b128 v[202:205], v168 offset:36864
	ds_read_b128 v[206:209], v168 offset:37888
	ds_read_b128 v[224:227], v168 offset:38912
	ds_read_b128 v[228:231], v168 offset:39936
	global_load_lds_dwordx4 v[232:233], off
	v_lshl_add_u64 v[232:233], s[34:35], 0, v[186:187]
	s_mov_b32 m0, s65
	s_nop 0
	global_load_lds_dwordx4 v[232:233], off
	s_waitcnt lgkmcnt(8)
	s_barrier
	s_waitcnt lgkmcnt(0)
	v_mfma_f32_16x16x32_bf16 v[124:127], v[136:139], v[172:175], v[124:127]
	v_mfma_f32_16x16x32_bf16 v[116:119], v[144:147], v[172:175], v[116:119]
	v_mfma_f32_16x16x32_bf16 v[108:111], v[136:139], v[194:197], v[108:111]
	v_mfma_f32_16x16x32_bf16 v[100:103], v[144:147], v[194:197], v[100:103]
	v_mfma_f32_16x16x32_bf16 v[92:95], v[136:139], v[202:205], v[92:95]
	v_mfma_f32_16x16x32_bf16 v[84:87], v[144:147], v[202:205], v[84:87]
	v_mfma_f32_16x16x32_bf16 v[76:79], v[136:139], v[224:227], v[76:79]
	v_mfma_f32_16x16x32_bf16 v[68:71], v[144:147], v[224:227], v[68:71]
	v_mfma_f32_16x16x32_bf16 v[124:127], v[140:143], v[190:193], v[124:127]
	v_mfma_f32_16x16x32_bf16 v[116:119], v[148:151], v[190:193], v[116:119]
	v_mfma_f32_16x16x32_bf16 v[108:111], v[140:143], v[198:201], v[108:111]
	v_mfma_f32_16x16x32_bf16 v[100:103], v[148:151], v[198:201], v[100:103]
	v_mfma_f32_16x16x32_bf16 v[92:95], v[140:143], v[206:209], v[92:95]
	v_mfma_f32_16x16x32_bf16 v[84:87], v[148:151], v[206:209], v[84:87]
	v_mfma_f32_16x16x32_bf16 v[76:79], v[140:143], v[228:231], v[76:79]
	v_mfma_f32_16x16x32_bf16 v[68:71], v[148:151], v[228:231], v[68:71]
	s_barrier
	s_add_i32 s33, 0, 0x1c000
	s_add_i32 s3, s3, s61
	v_add_u32_e32 v130, s33, v165
	v_lshl_add_u64 v[152:153], v[152:153], 0, s[86:87]
	s_mov_b32 m0, s3
	ds_read_b128 v[232:235], v130
	ds_read_b128 v[236:239], v130 offset:1024
	ds_read_b128 v[240:243], v130 offset:2048
	ds_read_b128 v[244:247], v130 offset:3072
	global_load_lds_dwordx4 v[152:153], off
	v_lshl_add_u64 v[152:153], v[248:249], 0, s[86:87]
	s_add_i32 m0, s3, 0x2000
	s_nop 0
	global_load_lds_dwordx4 v[152:153], off
	s_barrier
	s_waitcnt lgkmcnt(0)
	v_mfma_f32_16x16x32_bf16 v[120:123], v[232:235], v[172:175], v[120:123]
	v_mfma_f32_16x16x32_bf16 v[112:115], v[240:243], v[172:175], v[112:115]
	v_mfma_f32_16x16x32_bf16 v[104:107], v[232:235], v[194:197], v[104:107]
	v_mfma_f32_16x16x32_bf16 v[96:99], v[240:243], v[194:197], v[96:99]
	v_mfma_f32_16x16x32_bf16 v[88:91], v[232:235], v[202:205], v[88:91]
	v_mfma_f32_16x16x32_bf16 v[80:83], v[240:243], v[202:205], v[80:83]
	v_mfma_f32_16x16x32_bf16 v[72:75], v[232:235], v[224:227], v[72:75]
	v_mfma_f32_16x16x32_bf16 v[64:67], v[240:243], v[224:227], v[64:67]
	v_mfma_f32_16x16x32_bf16 v[120:123], v[236:239], v[190:193], v[120:123]
	v_mfma_f32_16x16x32_bf16 v[112:115], v[244:247], v[190:193], v[112:115]
	v_mfma_f32_16x16x32_bf16 v[104:107], v[236:239], v[198:201], v[104:107]
	v_mfma_f32_16x16x32_bf16 v[96:99], v[244:247], v[198:201], v[96:99]
	v_mfma_f32_16x16x32_bf16 v[88:91], v[236:239], v[206:209], v[88:91]
	v_mfma_f32_16x16x32_bf16 v[80:83], v[244:247], v[206:209], v[80:83]
	v_mfma_f32_16x16x32_bf16 v[72:75], v[236:239], v[228:231], v[72:75]
	v_mfma_f32_16x16x32_bf16 v[64:67], v[244:247], v[228:231], v[64:67]
	s_mov_b32 m0, s67
	v_lshl_add_u64 v[152:153], v[250:251], 0, s[86:87]
	s_barrier
	ds_read_b128 v[172:175], v168 offset:49152
	ds_read_b128 v[190:193], v168 offset:50176
	ds_read_b128 v[194:197], v168 offset:51200
	ds_read_b128 v[198:201], v168 offset:52224
	ds_read_b128 v[202:205], v168 offset:53248
	ds_read_b128 v[206:209], v168 offset:54272
	ds_read_b128 v[224:227], v168 offset:55296
	ds_read_b128 v[228:231], v168 offset:56320
	global_load_lds_dwordx4 v[152:153], off
	v_lshl_add_u64 v[152:153], v[252:253], 0, s[86:87]
	s_mov_b32 m0, s68
	s_nop 0
	global_load_lds_dwordx4 v[152:153], off
	s_barrier
	s_waitcnt lgkmcnt(0)
	v_mfma_f32_16x16x32_bf16 v[60:63], v[136:139], v[172:175], v[60:63]
	v_mfma_f32_16x16x32_bf16 v[52:55], v[144:147], v[172:175], v[52:55]
	v_mfma_f32_16x16x32_bf16 v[44:47], v[136:139], v[194:197], v[44:47]
	v_mfma_f32_16x16x32_bf16 v[36:39], v[144:147], v[194:197], v[36:39]
	v_mfma_f32_16x16x32_bf16 v[28:31], v[136:139], v[202:205], v[28:31]
	v_mfma_f32_16x16x32_bf16 v[20:23], v[144:147], v[202:205], v[20:23]
	v_mfma_f32_16x16x32_bf16 v[12:15], v[136:139], v[224:227], v[12:15]
	v_mfma_f32_16x16x32_bf16 v[4:7], v[144:147], v[224:227], v[4:7]
	v_mfma_f32_16x16x32_bf16 v[60:63], v[140:143], v[190:193], v[60:63]
	v_mfma_f32_16x16x32_bf16 v[52:55], v[148:151], v[190:193], v[52:55]
	v_mfma_f32_16x16x32_bf16 v[44:47], v[140:143], v[198:201], v[44:47]
	v_mfma_f32_16x16x32_bf16 v[36:39], v[148:151], v[198:201], v[36:39]
	v_mfma_f32_16x16x32_bf16 v[28:31], v[140:143], v[206:209], v[28:31]
	v_mfma_f32_16x16x32_bf16 v[20:23], v[148:151], v[206:209], v[20:23]
	v_mfma_f32_16x16x32_bf16 v[12:15], v[140:143], v[228:231], v[12:15]
	v_mfma_f32_16x16x32_bf16 v[4:7], v[148:151], v[228:231], v[4:7]
	s_barrier
	s_add_u32 s28, s28, 0x80080
	s_addc_u32 s29, s29, 0
	s_add_i32 s3, s33, s61
	v_lshl_add_u64 v[136:137], s[28:29], 0, v[184:185]
	s_mov_b32 m0, s3
	s_nop 0
	global_load_lds_dwordx4 v[136:137], off
	v_lshl_add_u64 v[136:137], s[28:29], 0, v[188:189]
	s_add_i32 m0, s3, 0x2000
	s_nop 0
	global_load_lds_dwordx4 v[136:137], off
	s_waitcnt vmcnt(6)
	s_barrier
	v_mfma_f32_16x16x32_bf16 v[56:59], v[232:235], v[172:175], v[56:59]
	v_mfma_f32_16x16x32_bf16 v[48:51], v[240:243], v[172:175], v[48:51]
	v_mfma_f32_16x16x32_bf16 v[40:43], v[232:235], v[194:197], v[40:43]
	v_mfma_f32_16x16x32_bf16 v[32:35], v[240:243], v[194:197], v[32:35]
	v_mfma_f32_16x16x32_bf16 v[24:27], v[232:235], v[202:205], v[24:27]
	v_mfma_f32_16x16x32_bf16 v[16:19], v[240:243], v[202:205], v[16:19]
	v_mfma_f32_16x16x32_bf16 v[8:11], v[232:235], v[224:227], v[8:11]
	v_mfma_f32_16x16x32_bf16 v[0:3], v[240:243], v[224:227], v[0:3]
	v_mfma_f32_16x16x32_bf16 v[56:59], v[236:239], v[190:193], v[56:59]
	v_mfma_f32_16x16x32_bf16 v[48:51], v[244:247], v[190:193], v[48:51]
	v_mfma_f32_16x16x32_bf16 v[40:43], v[236:239], v[198:201], v[40:43]
	v_mfma_f32_16x16x32_bf16 v[32:35], v[244:247], v[198:201], v[32:35]
	v_mfma_f32_16x16x32_bf16 v[24:27], v[236:239], v[206:209], v[24:27]
	v_mfma_f32_16x16x32_bf16 v[16:19], v[244:247], v[206:209], v[16:19]
	v_mfma_f32_16x16x32_bf16 v[8:11], v[236:239], v[228:231], v[8:11]
	v_mfma_f32_16x16x32_bf16 v[0:3], v[244:247], v[228:231], v[0:3]
	s_add_i32 vcc_lo, vcc_lo, 2
	s_add_u32 s10, s10, 0x100
	s_addc_u32 s11, s11, 0
	s_add_u32 s93, s93, 0x100
	s_addc_u32 s95, s95, 0
	s_cmp_gt_u32 vcc_lo, 29
	s_barrier
	s_cbranch_scc0 .LBB0_234
	v_lshl_add_u32 v136, s8, 8, v129
	s_cmp_gt_i32 s92, 15
	s_mov_b64 s[8:9], -1
	s_cbranch_scc0 .LBB0_285
	s_lshr_b32 s3, s92, 3
	s_add_i32 s3, s3, -2
	s_cmp_eq_u32 s3, 0
	s_cselect_b64 s[8:9], -1, 0
	v_mov_b32_e32 v130, 0xbfb8aa3b
	v_mov_b32_e32 v137, 0xc0135761
	s_cmp_eq_u32 s3, 1
	v_cndmask_b32_e64 v138, v130, v137, s[8:9]
	s_cselect_b64 s[28:29], -1, 0
	s_cmp_lg_u32 s3, 1
	v_cndmask_b32_e64 v140, 0, v170, s[8:9]
	s_cselect_b64 s[10:11], -1, 0
	v_mov_b32_e32 v141, v140
	v_mov_b32_e32 v139, v138
	s_and_b64 vcc, exec, s[28:29]
	s_cbranch_vccnz .LBB0_238
	v_pk_mul_f32 v[142:143], v[126:127], v[126:127]
	v_pk_mul_f32 v[144:145], v[124:125], v[124:125]
	v_pk_mul_f32 v[146:147], v[118:119], v[118:119]
	v_pk_mul_f32 v[148:149], v[116:117], v[116:117]
	v_pk_fma_f32 v[144:145], v[140:141], v[144:145], v[138:139]
	v_pk_fma_f32 v[142:143], v[140:141], v[142:143], v[138:139]
	v_pk_fma_f32 v[148:149], v[140:141], v[148:149], v[138:139]
	v_pk_fma_f32 v[146:147], v[140:141], v[146:147], v[138:139]
	v_pk_mul_f32 v[144:145], v[124:125], v[144:145]
	v_pk_mul_f32 v[142:143], v[126:127], v[142:143]
	v_pk_mul_f32 v[148:149], v[116:117], v[148:149]
	v_pk_mul_f32 v[146:147], v[118:119], v[146:147]
	v_exp_f32_e32 v144, v144
	v_exp_f32_e32 v145, v145
	v_exp_f32_e32 v142, v142
	v_exp_f32_e32 v143, v143
	v_exp_f32_e32 v148, v148
	v_exp_f32_e32 v149, v149
	v_exp_f32_e32 v146, v146
	v_exp_f32_e32 v147, v147
	v_pk_add_f32 v[144:145], v[144:145], 1.0 op_sel_hi:[1,0]
	v_pk_add_f32 v[142:143], v[142:143], 1.0 op_sel_hi:[1,0]
	v_pk_add_f32 v[148:149], v[148:149], 1.0 op_sel_hi:[1,0]
	v_pk_add_f32 v[146:147], v[146:147], 1.0 op_sel_hi:[1,0]
	v_rcp_f32_e32 v144, v144
	v_rcp_f32_e32 v145, v145
	v_rcp_f32_e32 v142, v142
	v_rcp_f32_e32 v143, v143
	v_rcp_f32_e32 v152, v148
	v_rcp_f32_e32 v153, v149
	v_rcp_f32_e32 v150, v146
	v_rcp_f32_e32 v151, v147
	v_pk_mul_f32 v[146:147], v[126:127], v[142:143]
	v_pk_mul_f32 v[148:149], v[124:125], v[144:145]
	v_pk_mul_f32 v[152:153], v[116:117], v[152:153]
	v_pk_mul_f32 v[150:151], v[118:119], v[150:151]
	s_branch .LBB0_239

.LBB0_558:
	ds_read_b128 v[40:43], v228
	ds_read_b128 v[44:47], v228 offset:1024
	ds_read_b128 v[52:55], v228 offset:2048
	ds_read_b128 v[60:63], v228 offset:3072
	s_add_u32 s3, s10, 0xfff80080
	s_addc_u32 s28, s11, -1
	s_cmp_eq_u32 s84, s86
	s_cselect_b32 s35, s41, s28
	s_cselect_b32 s34, s43, s3
	s_cselect_b32 s29, s39, s85
	s_cselect_b32 s28, s50, s51
	v_lshl_add_u64 v[198:199], s[10:11], 0, v[192:193]
	s_add_i32 m0, s61, 0xc000
	ds_read_b128 v[144:147], v229
	ds_read_b128 v[148:151], v229 offset:1024
	ds_read_b128 v[152:155], v229 offset:2048
	ds_read_b128 v[156:159], v229 offset:3072
	ds_read_b128 v[160:163], v229 offset:4096
	ds_read_b128 v[164:167], v229 offset:5120
	ds_read_b128 v[168:171], v229 offset:6144
	ds_read_b128 v[172:175], v229 offset:7168
	global_load_lds_dwordx4 v[198:199], off
	v_lshl_add_u64 v[198:199], s[10:11], 0, v[194:195]
	s_add_i32 m0, s61, 0xe000
	s_nop 0
	global_load_lds_dwordx4 v[198:199], off
	s_waitcnt lgkmcnt(8)
	s_barrier
	s_waitcnt lgkmcnt(0)
	v_mfma_f32_16x16x32_bf16 v[140:143], v[40:43], v[144:147], v[140:143]
	v_mfma_f32_16x16x32_bf16 v[136:139], v[52:55], v[144:147], v[136:139]
	v_mfma_f32_16x16x32_bf16 v[124:127], v[40:43], v[152:155], v[124:127]
	v_mfma_f32_16x16x32_bf16 v[120:123], v[52:55], v[152:155], v[120:123]
	v_mfma_f32_16x16x32_bf16 v[108:111], v[40:43], v[160:163], v[108:111]
	v_mfma_f32_16x16x32_bf16 v[104:107], v[52:55], v[160:163], v[104:107]
	v_mfma_f32_16x16x32_bf16 v[92:95], v[40:43], v[168:171], v[92:95]
	v_mfma_f32_16x16x32_bf16 v[88:91], v[52:55], v[168:171], v[88:91]
	v_mfma_f32_16x16x32_bf16 v[140:143], v[44:47], v[148:151], v[140:143]
	v_mfma_f32_16x16x32_bf16 v[136:139], v[60:63], v[148:151], v[136:139]
	v_mfma_f32_16x16x32_bf16 v[124:127], v[44:47], v[156:159], v[124:127]
	v_mfma_f32_16x16x32_bf16 v[120:123], v[60:63], v[156:159], v[120:123]
	v_mfma_f32_16x16x32_bf16 v[108:111], v[44:47], v[164:167], v[108:111]
	v_mfma_f32_16x16x32_bf16 v[104:107], v[60:63], v[164:167], v[104:107]
	v_mfma_f32_16x16x32_bf16 v[92:95], v[44:47], v[172:175], v[92:95]
	v_mfma_f32_16x16x32_bf16 v[88:91], v[60:63], v[172:175], v[88:91]
	s_barrier
	s_add_i32 s3, s79, s69
	v_lshl_add_u64 v[236:237], s[28:29], 0, v[184:185]
	s_mov_b32 m0, s3
	ds_read_b128 v[198:201], v230
	ds_read_b128 v[202:205], v230 offset:1024
	ds_read_b128 v[206:209], v230 offset:2048
	ds_read_b128 v[232:235], v230 offset:3072
	global_load_lds_dwordx4 v[236:237], off
	v_lshl_add_u64 v[238:239], s[28:29], 0, v[188:189]
	s_add_i32 m0, s3, 0x2000
	s_nop 0
	global_load_lds_dwordx4 v[238:239], off
	s_barrier
	s_waitcnt lgkmcnt(0)
	v_mfma_f32_16x16x32_bf16 v[132:135], v[198:201], v[144:147], v[132:135]
	v_mfma_f32_16x16x32_bf16 v[128:131], v[206:209], v[144:147], v[128:131]
	v_mfma_f32_16x16x32_bf16 v[116:119], v[198:201], v[152:155], v[116:119]
	v_mfma_f32_16x16x32_bf16 v[112:115], v[206:209], v[152:155], v[112:115]
	v_mfma_f32_16x16x32_bf16 v[100:103], v[198:201], v[160:163], v[100:103]
	v_mfma_f32_16x16x32_bf16 v[96:99], v[206:209], v[160:163], v[96:99]
	v_mfma_f32_16x16x32_bf16 v[84:87], v[198:201], v[168:171], v[84:87]
	v_mfma_f32_16x16x32_bf16 v[80:83], v[206:209], v[168:171], v[80:83]
	v_mfma_f32_16x16x32_bf16 v[132:135], v[202:205], v[148:151], v[132:135]
	v_mfma_f32_16x16x32_bf16 v[128:131], v[232:235], v[148:151], v[128:131]
	v_mfma_f32_16x16x32_bf16 v[116:119], v[202:205], v[156:159], v[116:119]
	v_mfma_f32_16x16x32_bf16 v[112:115], v[232:235], v[156:159], v[112:115]
	v_mfma_f32_16x16x32_bf16 v[100:103], v[202:205], v[164:167], v[100:103]
	v_mfma_f32_16x16x32_bf16 v[96:99], v[232:235], v[164:167], v[96:99]
	v_mfma_f32_16x16x32_bf16 v[84:87], v[202:205], v[172:175], v[84:87]
	v_mfma_f32_16x16x32_bf16 v[80:83], v[232:235], v[172:175], v[80:83]
	s_mov_b32 m0, s61
	v_lshl_add_u64 v[240:241], s[34:35], 0, v[182:183]
	s_barrier
	ds_read_b128 v[144:147], v229 offset:16384
	ds_read_b128 v[148:151], v229 offset:17408
	ds_read_b128 v[152:155], v229 offset:18432
	ds_read_b128 v[156:159], v229 offset:19456
	ds_read_b128 v[160:163], v229 offset:20480
	ds_read_b128 v[164:167], v229 offset:21504
	ds_read_b128 v[168:171], v229 offset:22528
	ds_read_b128 v[172:175], v229 offset:23552
	global_load_lds_dwordx4 v[240:241], off
	v_lshl_add_u64 v[242:243], s[34:35], 0, v[186:187]
	s_mov_b32 m0, s63
	s_nop 0
	global_load_lds_dwordx4 v[242:243], off
	s_barrier
	s_waitcnt lgkmcnt(0)
	v_mfma_f32_16x16x32_bf16 v[76:79], v[40:43], v[144:147], v[76:79]
	v_mfma_f32_16x16x32_bf16 v[72:75], v[52:55], v[144:147], v[72:75]
	v_mfma_f32_16x16x32_bf16 v[56:59], v[40:43], v[152:155], v[56:59]
	v_mfma_f32_16x16x32_bf16 v[48:51], v[52:55], v[152:155], v[48:51]
	v_mfma_f32_16x16x32_bf16 v[28:31], v[40:43], v[160:163], v[28:31]
	v_mfma_f32_16x16x32_bf16 v[24:27], v[52:55], v[160:163], v[24:27]
	v_mfma_f32_16x16x32_bf16 v[12:15], v[40:43], v[168:171], v[12:15]
	v_mfma_f32_16x16x32_bf16 v[8:11], v[52:55], v[168:171], v[8:11]
	v_mfma_f32_16x16x32_bf16 v[76:79], v[44:47], v[148:151], v[76:79]
	v_mfma_f32_16x16x32_bf16 v[72:75], v[60:63], v[148:151], v[72:75]
	v_mfma_f32_16x16x32_bf16 v[56:59], v[44:47], v[156:159], v[56:59]
	v_mfma_f32_16x16x32_bf16 v[48:51], v[60:63], v[156:159], v[48:51]
	v_mfma_f32_16x16x32_bf16 v[28:31], v[44:47], v[164:167], v[28:31]
	v_mfma_f32_16x16x32_bf16 v[24:27], v[60:63], v[164:167], v[24:27]
	v_mfma_f32_16x16x32_bf16 v[12:15], v[44:47], v[172:175], v[12:15]
	v_mfma_f32_16x16x32_bf16 v[8:11], v[60:63], v[172:175], v[8:11]
	s_barrier
	s_add_u32 s88, s28, 0x80000
	s_addc_u32 s89, s29, 0
	s_add_i32 s3, s80, s69
	v_lshl_add_u64 v[40:41], s[88:89], 0, v[184:185]
	s_mov_b32 m0, s3
	s_nop 0
	global_load_lds_dwordx4 v[40:41], off
	v_lshl_add_u64 v[40:41], s[88:89], 0, v[188:189]
	s_add_i32 m0, s3, 0x2000
	s_nop 0
	global_load_lds_dwordx4 v[40:41], off
	s_waitcnt vmcnt(6)
	s_barrier
	v_mfma_f32_16x16x32_bf16 v[36:39], v[198:201], v[152:155], v[36:39]
	v_mfma_f32_16x16x32_bf16 v[32:35], v[206:209], v[152:155], v[32:35]
	v_mfma_f32_16x16x32_bf16 v[20:23], v[198:201], v[160:163], v[20:23]
	v_mfma_f32_16x16x32_bf16 v[16:19], v[206:209], v[160:163], v[16:19]
	v_mfma_f32_16x16x32_bf16 v[4:7], v[198:201], v[168:171], v[4:7]
	v_mfma_f32_16x16x32_bf16 v[0:3], v[206:209], v[168:171], v[0:3]
	v_mfma_f32_16x16x32_bf16 v[40:43], v[198:201], v[144:147], v[68:71]
	v_mfma_f32_16x16x32_bf16 v[44:47], v[206:209], v[144:147], v[64:67]
	v_mfma_f32_16x16x32_bf16 v[36:39], v[202:205], v[156:159], v[36:39]
	v_mfma_f32_16x16x32_bf16 v[32:35], v[232:235], v[156:159], v[32:35]
	v_mfma_f32_16x16x32_bf16 v[20:23], v[202:205], v[164:167], v[20:23]
	v_mfma_f32_16x16x32_bf16 v[16:19], v[232:235], v[164:167], v[16:19]
	v_mfma_f32_16x16x32_bf16 v[4:7], v[202:205], v[172:175], v[4:7]
	v_mfma_f32_16x16x32_bf16 v[0:3], v[232:235], v[172:175], v[0:3]
	v_mfma_f32_16x16x32_bf16 v[40:43], v[202:205], v[148:151], v[40:43]
	v_mfma_f32_16x16x32_bf16 v[44:47], v[232:235], v[148:151], v[44:47]
	s_add_i32 s3, 0, 0x18000
	v_add_u32_e32 v68, s3, v226
	s_barrier
	ds_read_b128 v[52:55], v68
	ds_read_b128 v[60:63], v68 offset:1024
	ds_read_b128 v[64:67], v68 offset:2048
	ds_read_b128 v[68:71], v68 offset:3072
	s_add_u32 s34, s34, 0x80000
	s_addc_u32 s35, s35, 0
	s_mov_b32 m0, s67
	v_lshl_add_u64 v[198:199], s[34:35], 0, v[182:183]
	ds_read_b128 v[144:147], v229 offset:32768
	ds_read_b128 v[148:151], v229 offset:33792
	ds_read_b128 v[152:155], v229 offset:34816
	ds_read_b128 v[156:159], v229 offset:35840
	ds_read_b128 v[160:163], v229 offset:36864
	ds_read_b128 v[164:167], v229 offset:37888
	ds_read_b128 v[168:171], v229 offset:38912
	ds_read_b128 v[172:175], v229 offset:39936
	global_load_lds_dwordx4 v[198:199], off
	v_lshl_add_u64 v[198:199], s[34:35], 0, v[186:187]
	s_mov_b32 m0, s70
	s_nop 0
	global_load_lds_dwordx4 v[198:199], off
	s_waitcnt lgkmcnt(8)
	s_barrier
	s_waitcnt lgkmcnt(0)
	v_mfma_f32_16x16x32_bf16 v[140:143], v[52:55], v[144:147], v[140:143]
	v_mfma_f32_16x16x32_bf16 v[136:139], v[64:67], v[144:147], v[136:139]
	v_mfma_f32_16x16x32_bf16 v[124:127], v[52:55], v[152:155], v[124:127]
	v_mfma_f32_16x16x32_bf16 v[120:123], v[64:67], v[152:155], v[120:123]
	v_mfma_f32_16x16x32_bf16 v[108:111], v[52:55], v[160:163], v[108:111]
	v_mfma_f32_16x16x32_bf16 v[104:107], v[64:67], v[160:163], v[104:107]
	v_mfma_f32_16x16x32_bf16 v[92:95], v[52:55], v[168:171], v[92:95]
	v_mfma_f32_16x16x32_bf16 v[88:91], v[64:67], v[168:171], v[88:91]
	v_mfma_f32_16x16x32_bf16 v[140:143], v[60:63], v[148:151], v[140:143]
	v_mfma_f32_16x16x32_bf16 v[136:139], v[68:71], v[148:151], v[136:139]
	v_mfma_f32_16x16x32_bf16 v[124:127], v[60:63], v[156:159], v[124:127]
	v_mfma_f32_16x16x32_bf16 v[120:123], v[68:71], v[156:159], v[120:123]
	v_mfma_f32_16x16x32_bf16 v[108:111], v[60:63], v[164:167], v[108:111]
	v_mfma_f32_16x16x32_bf16 v[104:107], v[68:71], v[164:167], v[104:107]
	v_mfma_f32_16x16x32_bf16 v[92:95], v[60:63], v[172:175], v[92:95]
	v_mfma_f32_16x16x32_bf16 v[88:91], v[68:71], v[172:175], v[88:91]
	s_barrier
	s_add_i32 s34, 0, 0x1c000
	s_add_i32 s3, s3, s69
	v_add_u32_e32 v231, s34, v226
	v_lshl_add_u64 v[236:237], v[236:237], 0, s[22:23]
	s_mov_b32 m0, s3
	ds_read_b128 v[198:201], v231
	ds_read_b128 v[202:205], v231 offset:1024
	ds_read_b128 v[206:209], v231 offset:2048
	ds_read_b128 v[232:235], v231 offset:3072
	global_load_lds_dwordx4 v[236:237], off
	v_lshl_add_u64 v[236:237], v[238:239], 0, s[22:23]
	s_add_i32 m0, s3, 0x2000
	s_nop 0
	global_load_lds_dwordx4 v[236:237], off
	s_barrier
	s_waitcnt lgkmcnt(0)
	v_mfma_f32_16x16x32_bf16 v[132:135], v[198:201], v[144:147], v[132:135]
	v_mfma_f32_16x16x32_bf16 v[128:131], v[206:209], v[144:147], v[128:131]
	v_mfma_f32_16x16x32_bf16 v[116:119], v[198:201], v[152:155], v[116:119]
	v_mfma_f32_16x16x32_bf16 v[112:115], v[206:209], v[152:155], v[112:115]
	v_mfma_f32_16x16x32_bf16 v[100:103], v[198:201], v[160:163], v[100:103]
	v_mfma_f32_16x16x32_bf16 v[96:99], v[206:209], v[160:163], v[96:99]
	v_mfma_f32_16x16x32_bf16 v[84:87], v[198:201], v[168:171], v[84:87]
	v_mfma_f32_16x16x32_bf16 v[80:83], v[206:209], v[168:171], v[80:83]
	v_mfma_f32_16x16x32_bf16 v[132:135], v[202:205], v[148:151], v[132:135]
	v_mfma_f32_16x16x32_bf16 v[128:131], v[232:235], v[148:151], v[128:131]
	v_mfma_f32_16x16x32_bf16 v[116:119], v[202:205], v[156:159], v[116:119]
	v_mfma_f32_16x16x32_bf16 v[112:115], v[232:235], v[156:159], v[112:115]
	v_mfma_f32_16x16x32_bf16 v[100:103], v[202:205], v[164:167], v[100:103]
	v_mfma_f32_16x16x32_bf16 v[96:99], v[232:235], v[164:167], v[96:99]
	v_mfma_f32_16x16x32_bf16 v[84:87], v[202:205], v[172:175], v[84:87]
	v_mfma_f32_16x16x32_bf16 v[80:83], v[232:235], v[172:175], v[80:83]
	s_mov_b32 m0, s71
	v_lshl_add_u64 v[236:237], v[240:241], 0, s[22:23]
	s_barrier
	ds_read_b128 v[144:147], v229 offset:49152
	ds_read_b128 v[148:151], v229 offset:50176
	ds_read_b128 v[152:155], v229 offset:51200
	ds_read_b128 v[156:159], v229 offset:52224
	ds_read_b128 v[160:163], v229 offset:53248
	ds_read_b128 v[164:167], v229 offset:54272
	ds_read_b128 v[168:171], v229 offset:55296
	ds_read_b128 v[172:175], v229 offset:56320
	global_load_lds_dwordx4 v[236:237], off
	v_lshl_add_u64 v[236:237], v[242:243], 0, s[22:23]
	s_mov_b32 m0, s74
	s_nop 0
	global_load_lds_dwordx4 v[236:237], off
	s_barrier
	s_waitcnt lgkmcnt(0)
	v_mfma_f32_16x16x32_bf16 v[76:79], v[52:55], v[144:147], v[76:79]
	v_mfma_f32_16x16x32_bf16 v[72:75], v[64:67], v[144:147], v[72:75]
	v_mfma_f32_16x16x32_bf16 v[56:59], v[52:55], v[152:155], v[56:59]
	v_mfma_f32_16x16x32_bf16 v[48:51], v[64:67], v[152:155], v[48:51]
	v_mfma_f32_16x16x32_bf16 v[28:31], v[52:55], v[160:163], v[28:31]
	v_mfma_f32_16x16x32_bf16 v[24:27], v[64:67], v[160:163], v[24:27]
	v_mfma_f32_16x16x32_bf16 v[12:15], v[52:55], v[168:171], v[12:15]
	v_mfma_f32_16x16x32_bf16 v[8:11], v[64:67], v[168:171], v[8:11]
	v_mfma_f32_16x16x32_bf16 v[76:79], v[60:63], v[148:151], v[76:79]
	v_mfma_f32_16x16x32_bf16 v[72:75], v[68:71], v[148:151], v[72:75]
	v_mfma_f32_16x16x32_bf16 v[56:59], v[60:63], v[156:159], v[56:59]
	v_mfma_f32_16x16x32_bf16 v[48:51], v[68:71], v[156:159], v[48:51]
	v_mfma_f32_16x16x32_bf16 v[28:31], v[60:63], v[164:167], v[28:31]
	v_mfma_f32_16x16x32_bf16 v[24:27], v[68:71], v[164:167], v[24:27]
	v_mfma_f32_16x16x32_bf16 v[12:15], v[60:63], v[172:175], v[12:15]
	v_mfma_f32_16x16x32_bf16 v[8:11], v[68:71], v[172:175], v[8:11]
	s_barrier
	s_add_u32 s28, s28, 0x80080
	s_addc_u32 s29, s29, 0
	s_add_i32 s3, s34, s69
	v_lshl_add_u64 v[52:53], s[28:29], 0, v[184:185]
	s_mov_b32 m0, s3
	s_nop 0
	global_load_lds_dwordx4 v[52:53], off
	v_lshl_add_u64 v[52:53], s[28:29], 0, v[188:189]
	s_add_i32 m0, s3, 0x2000
	s_nop 0
	global_load_lds_dwordx4 v[52:53], off
	s_waitcnt vmcnt(6)
	s_barrier
	v_mfma_f32_16x16x32_bf16 v[40:43], v[198:201], v[144:147], v[40:43]
	v_mfma_f32_16x16x32_bf16 v[68:71], v[202:205], v[148:151], v[40:43]
	v_mfma_f32_16x16x32_bf16 v[40:43], v[206:209], v[144:147], v[44:47]
	v_mfma_f32_16x16x32_bf16 v[36:39], v[198:201], v[152:155], v[36:39]
	v_mfma_f32_16x16x32_bf16 v[32:35], v[206:209], v[152:155], v[32:35]
	v_mfma_f32_16x16x32_bf16 v[20:23], v[198:201], v[160:163], v[20:23]
	v_mfma_f32_16x16x32_bf16 v[16:19], v[206:209], v[160:163], v[16:19]
	v_mfma_f32_16x16x32_bf16 v[4:7], v[198:201], v[168:171], v[4:7]
	v_mfma_f32_16x16x32_bf16 v[0:3], v[206:209], v[168:171], v[0:3]
	v_mfma_f32_16x16x32_bf16 v[64:67], v[232:235], v[148:151], v[40:43]
	v_mfma_f32_16x16x32_bf16 v[36:39], v[202:205], v[156:159], v[36:39]
	v_mfma_f32_16x16x32_bf16 v[32:35], v[232:235], v[156:159], v[32:35]
	v_mfma_f32_16x16x32_bf16 v[20:23], v[202:205], v[164:167], v[20:23]
	v_mfma_f32_16x16x32_bf16 v[16:19], v[232:235], v[164:167], v[16:19]
	v_mfma_f32_16x16x32_bf16 v[4:7], v[202:205], v[172:175], v[4:7]
	v_mfma_f32_16x16x32_bf16 v[0:3], v[232:235], v[172:175], v[0:3]
	s_add_i32 s3, s86, 2
	s_add_u32 s10, s10, 0x100
	s_addc_u32 s11, s11, 0
	s_add_u32 s51, s51, 0x100
	s_addc_u32 s85, s85, 0
	s_cmp_ge_u32 s86, s84
	s_mov_b32 s86, s3
	s_barrier
	s_cbranch_scc0 .LBB0_558
	s_cmp_eq_u32 s84, 32
	s_cselect_b64 s[50:51], -1, 0
	s_mov_b64 s[10:11], -1
	s_and_b64 vcc, exec, s[50:51]
	s_cbranch_vccnz .LBB0_562
	s_lshl_b32 s3, s84, 6
	s_sext_i32_i16 s3, s3
	v_cvt_f32_i32_e32 v40, s3
	v_cvt_f32_i32_e32 v41, s66
	s_xor_b32 s3, s66, s3
	s_ashr_i32 s3, s3, 30
	v_rcp_iflag_f32_e32 v43, v40
	s_or_b32 s3, s3, 1
	v_cvt_pk_bf16_f32 v42, v140, v141
	v_cvt_pk_bf16_f32 v44, v136, v137
	v_mul_f32_e32 v43, v41, v43
	v_trunc_f32_e32 v43, v43
	v_fma_f32 v41, -v43, v40, v41
	v_cvt_i32_f32_e32 v43, v43
	v_cmp_ge_f32_e64 s[10:11], |v41|, |v40|
	s_and_b64 s[10:11], s[10:11], exec
	s_cselect_b32 s3, s3, 0
	v_add_u32_e32 v40, s3, v43
	v_bfe_i32 v40, v40, 0, 16
	v_ashrrev_i32_e32 v41, 31, v40
	v_lshlrev_b64 v[40:41], 22, v[40:41]
	v_lshl_add_u64 v[40:41], v[190:191], 0, v[40:41]
	v_cvt_pk_bf16_f32 v43, v142, v143
	v_cvt_pk_bf16_f32 v45, v138, v139
	s_mov_b64 s[10:11], 0x400
	global_store_dwordx4 v[40:41], v[42:45], off sc1
	s_nop 2
	v_cvt_pk_bf16_f32 v42, v132, v133
	v_cvt_pk_bf16_f32 v43, v134, v135
	v_cvt_pk_bf16_f32 v44, v128, v129
	v_cvt_pk_bf16_f32 v45, v130, v131
	v_lshl_add_u64 v[46:47], v[40:41], 0, s[10:11]
	global_store_dwordx4 v[46:47], v[42:45], off sc1
	s_nop 2
	s_mov_b64 s[10:11], 0x800
	v_cvt_pk_bf16_f32 v42, v124, v125
	v_cvt_pk_bf16_f32 v43, v126, v127
	v_cvt_pk_bf16_f32 v44, v120, v121
	v_cvt_pk_bf16_f32 v45, v122, v123
	v_lshl_add_u64 v[46:47], v[40:41], 0, s[10:11]
	global_store_dwordx4 v[46:47], v[42:45], off sc1
	s_nop 2
	s_mov_b64 s[10:11], 0xc00
	v_cvt_pk_bf16_f32 v42, v116, v117
	v_cvt_pk_bf16_f32 v43, v118, v119
	v_cvt_pk_bf16_f32 v44, v112, v113
	v_cvt_pk_bf16_f32 v45, v114, v115
	v_lshl_add_u64 v[46:47], v[40:41], 0, s[10:11]
	global_store_dwordx4 v[46:47], v[42:45], off sc1
	s_nop 2
	s_mov_b64 s[10:11], 0x1000
	v_cvt_pk_bf16_f32 v42, v108, v109
	v_cvt_pk_bf16_f32 v43, v110, v111
	v_cvt_pk_bf16_f32 v44, v104, v105
	v_cvt_pk_bf16_f32 v45, v106, v107
	v_lshl_add_u64 v[46:47], v[40:41], 0, s[10:11]
	global_store_dwordx4 v[46:47], v[42:45], off sc1
	s_nop 2
	s_mov_b64 s[10:11], 0x1400
	v_cvt_pk_bf16_f32 v42, v100, v101
	v_cvt_pk_bf16_f32 v43, v102, v103
	v_cvt_pk_bf16_f32 v44, v96, v97
	v_cvt_pk_bf16_f32 v45, v98, v99
	v_lshl_add_u64 v[46:47], v[40:41], 0, s[10:11]
	global_store_dwordx4 v[46:47], v[42:45], off sc1
	s_nop 2
	s_mov_b64 s[10:11], 0x1800
	v_cvt_pk_bf16_f32 v42, v92, v93
	v_cvt_pk_bf16_f32 v43, v94, v95
	v_cvt_pk_bf16_f32 v44, v88, v89
	v_cvt_pk_bf16_f32 v45, v90, v91
	v_lshl_add_u64 v[46:47], v[40:41], 0, s[10:11]
	global_store_dwordx4 v[46:47], v[42:45], off sc1
	s_nop 2
	s_mov_b64 s[10:11], 0x1c00
	v_cvt_pk_bf16_f32 v42, v84, v85
	v_cvt_pk_bf16_f32 v43, v86, v87
	v_cvt_pk_bf16_f32 v44, v80, v81
	v_cvt_pk_bf16_f32 v45, v82, v83
	v_lshl_add_u64 v[46:47], v[40:41], 0, s[10:11]
	global_store_dwordx4 v[46:47], v[42:45], off sc1
	s_nop 2
	s_mov_b64 s[10:11], 0x2000
	v_cvt_pk_bf16_f32 v42, v76, v77
	v_cvt_pk_bf16_f32 v43, v78, v79
	v_cvt_pk_bf16_f32 v44, v72, v73
	v_cvt_pk_bf16_f32 v45, v74, v75
	v_lshl_add_u64 v[46:47], v[40:41], 0, s[10:11]
	global_store_dwordx4 v[46:47], v[42:45], off sc1
	s_nop 2
	s_mov_b64 s[10:11], 0x2400
	v_cvt_pk_bf16_f32 v42, v68, v69
	v_cvt_pk_bf16_f32 v43, v70, v71
	v_cvt_pk_bf16_f32 v44, v64, v65
	v_cvt_pk_bf16_f32 v45, v66, v67
	v_lshl_add_u64 v[46:47], v[40:41], 0, s[10:11]
	global_store_dwordx4 v[46:47], v[42:45], off sc1
	s_nop 2
	s_mov_b64 s[10:11], 0x2800
	v_cvt_pk_bf16_f32 v42, v56, v57
	v_cvt_pk_bf16_f32 v43, v58, v59
	v_cvt_pk_bf16_f32 v44, v48, v49
	v_cvt_pk_bf16_f32 v45, v50, v51
	v_lshl_add_u64 v[46:47], v[40:41], 0, s[10:11]
	global_store_dwordx4 v[46:47], v[42:45], off sc1
	s_nop 2
	s_mov_b64 s[10:11], 0x2c00
	v_cvt_pk_bf16_f32 v42, v36, v37
	v_cvt_pk_bf16_f32 v43, v38, v39
	v_cvt_pk_bf16_f32 v44, v32, v33
	v_cvt_pk_bf16_f32 v45, v34, v35
	v_lshl_add_u64 v[46:47], v[40:41], 0, s[10:11]
	global_store_dwordx4 v[46:47], v[42:45], off sc1
	s_nop 2
	s_mov_b64 s[10:11], 0x3000
	v_cvt_pk_bf16_f32 v42, v28, v29
	v_cvt_pk_bf16_f32 v43, v30, v31
	v_cvt_pk_bf16_f32 v44, v24, v25
	v_cvt_pk_bf16_f32 v45, v26, v27
	v_lshl_add_u64 v[46:47], v[40:41], 0, s[10:11]
	global_store_dwordx4 v[46:47], v[42:45], off sc1
	s_nop 2
	s_mov_b64 s[10:11], 0x3400
	v_cvt_pk_bf16_f32 v42, v20, v21
	v_cvt_pk_bf16_f32 v43, v22, v23
	v_cvt_pk_bf16_f32 v44, v16, v17
	v_cvt_pk_bf16_f32 v45, v18, v19
	v_lshl_add_u64 v[46:47], v[40:41], 0, s[10:11]
	global_store_dwordx4 v[46:47], v[42:45], off sc1
	s_nop 2
	s_mov_b64 s[10:11], 0x3800
	v_cvt_pk_bf16_f32 v42, v12, v13
	v_cvt_pk_bf16_f32 v43, v14, v15
	v_cvt_pk_bf16_f32 v44, v8, v9
	v_cvt_pk_bf16_f32 v45, v10, v11
	v_lshl_add_u64 v[46:47], v[40:41], 0, s[10:11]
	global_store_dwordx4 v[46:47], v[42:45], off sc1
	s_nop 2
	v_cvt_pk_bf16_f32 v42, v4, v5
	v_cvt_pk_bf16_f32 v43, v6, v7
	v_cvt_pk_bf16_f32 v44, v0, v1
	v_cvt_pk_bf16_f32 v45, v2, v3
	v_lshl_add_u64 v[40:41], v[40:41], 0, s[26:27]
	global_store_dwordx4 v[40:41], v[42:45], off sc1
	s_nop 2
	s_cbranch_execz .LBB0_563

.LBB0_640:
	s_add_i32 s89, s89, 2
	v_add_u32_e32 v56, s71, v139
	s_add_u32 s3, s22, s34
	ds_read_b128 v[150:153], v56
	ds_read_b128 v[154:157], v56 offset:1024
	ds_read_b128 v[158:161], v56 offset:2048
	ds_read_b128 v[162:165], v56 offset:3072
	s_addc_u32 s36, s23, s35
	s_add_u32 s3, s3, 0x100
	s_addc_u32 s36, s36, 0
	s_add_u32 s90, s83, s34
	s_addc_u32 s37, s84, s35
	s_cmp_eq_u32 s88, s34
	s_cselect_b32 s39, s11, s36
	s_cselect_b32 s38, s85, s3
	s_cselect_b32 s37, s86, s37
	s_cselect_b32 s36, s87, s90
	s_mov_b32 m0, s73
	v_lshl_add_u64 v[174:175], v[58:59], 0, s[34:35]
	ds_read_b128 v[166:169], v133
	ds_read_b128 v[170:173], v133 offset:1024
	ds_read_b128 v[182:185], v133 offset:2048
	ds_read_b128 v[186:189], v133 offset:3072
	ds_read_b128 v[190:193], v133 offset:4096
	ds_read_b128 v[194:197], v133 offset:5120
	ds_read_b128 v[198:201], v133 offset:6144
	ds_read_b128 v[202:205], v133 offset:7168
	global_load_lds_dwordx4 v[174:175], off
	v_lshl_add_u64 v[174:175], v[146:147], 0, s[34:35]
	s_mov_b32 m0, s74
	s_nop 0
	global_load_lds_dwordx4 v[174:175], off
	s_waitcnt lgkmcnt(8)
	s_barrier
	s_waitcnt lgkmcnt(0)
	v_mfma_f32_16x16x32_bf16 v[128:131], v[150:153], v[166:169], v[128:131]
	v_mfma_f32_16x16x32_bf16 v[124:127], v[158:161], v[166:169], v[124:127]
	v_mfma_f32_16x16x32_bf16 v[112:115], v[150:153], v[182:185], v[112:115]
	v_mfma_f32_16x16x32_bf16 v[108:111], v[158:161], v[182:185], v[108:111]
	v_mfma_f32_16x16x32_bf16 v[96:99], v[150:153], v[190:193], v[96:99]
	v_mfma_f32_16x16x32_bf16 v[92:95], v[158:161], v[190:193], v[92:95]
	v_mfma_f32_16x16x32_bf16 v[80:83], v[150:153], v[198:201], v[80:83]
	v_mfma_f32_16x16x32_bf16 v[76:79], v[158:161], v[198:201], v[76:79]
	v_mfma_f32_16x16x32_bf16 v[128:131], v[154:157], v[170:173], v[128:131]
	v_mfma_f32_16x16x32_bf16 v[124:127], v[162:165], v[170:173], v[124:127]
	v_mfma_f32_16x16x32_bf16 v[112:115], v[154:157], v[186:189], v[112:115]
	v_mfma_f32_16x16x32_bf16 v[108:111], v[162:165], v[186:189], v[108:111]
	v_mfma_f32_16x16x32_bf16 v[96:99], v[154:157], v[194:197], v[96:99]
	v_mfma_f32_16x16x32_bf16 v[92:95], v[162:165], v[194:197], v[92:95]
	v_mfma_f32_16x16x32_bf16 v[80:83], v[154:157], v[202:205], v[80:83]
	v_mfma_f32_16x16x32_bf16 v[76:79], v[162:165], v[202:205], v[76:79]
	s_barrier
	s_mov_b32 m0, s75
	v_add_u32_e32 v56, s72, v139
	v_lshl_add_u64 v[174:175], s[36:37], 0, v[134:135]
	ds_read_b128 v[206:209], v56
	ds_read_b128 v[214:217], v56 offset:1024
	ds_read_b128 v[218:221], v56 offset:2048
	ds_read_b128 v[222:225], v56 offset:3072
	global_load_lds_dwordx4 v[174:175], off
	v_lshl_add_u64 v[226:227], s[36:37], 0, v[136:137]
	s_mov_b32 m0, s76
	s_nop 0
	global_load_lds_dwordx4 v[226:227], off
	s_barrier
	s_waitcnt lgkmcnt(0)
	v_mfma_f32_16x16x32_bf16 v[120:123], v[206:209], v[166:169], v[120:123]
	v_mfma_f32_16x16x32_bf16 v[116:119], v[218:221], v[166:169], v[116:119]
	v_mfma_f32_16x16x32_bf16 v[104:107], v[206:209], v[182:185], v[104:107]
	v_mfma_f32_16x16x32_bf16 v[100:103], v[218:221], v[182:185], v[100:103]
	v_mfma_f32_16x16x32_bf16 v[88:91], v[206:209], v[190:193], v[88:91]
	v_mfma_f32_16x16x32_bf16 v[84:87], v[218:221], v[190:193], v[84:87]
	v_mfma_f32_16x16x32_bf16 v[72:75], v[206:209], v[198:201], v[72:75]
	v_mfma_f32_16x16x32_bf16 v[68:71], v[218:221], v[198:201], v[68:71]
	v_mfma_f32_16x16x32_bf16 v[120:123], v[214:217], v[170:173], v[120:123]
	v_mfma_f32_16x16x32_bf16 v[116:119], v[222:225], v[170:173], v[116:119]
	v_mfma_f32_16x16x32_bf16 v[104:107], v[214:217], v[186:189], v[104:107]
	v_mfma_f32_16x16x32_bf16 v[100:103], v[222:225], v[186:189], v[100:103]
	v_mfma_f32_16x16x32_bf16 v[88:91], v[214:217], v[194:197], v[88:91]
	v_mfma_f32_16x16x32_bf16 v[84:87], v[222:225], v[194:197], v[84:87]
	v_mfma_f32_16x16x32_bf16 v[72:75], v[214:217], v[202:205], v[72:75]
	v_mfma_f32_16x16x32_bf16 v[68:71], v[222:225], v[202:205], v[68:71]
	s_mov_b32 m0, s44
	v_lshl_add_u64 v[228:229], s[38:39], 0, v[134:135]
	s_barrier
	ds_read_b128 v[166:169], v133 offset:16384
	ds_read_b128 v[170:173], v133 offset:17408
	ds_read_b128 v[182:185], v133 offset:18432
	ds_read_b128 v[186:189], v133 offset:19456
	ds_read_b128 v[190:193], v133 offset:20480
	ds_read_b128 v[194:197], v133 offset:21504
	ds_read_b128 v[198:201], v133 offset:22528
	ds_read_b128 v[202:205], v133 offset:23552
	global_load_lds_dwordx4 v[228:229], off
	v_lshl_add_u64 v[230:231], s[38:39], 0, v[136:137]
	s_mov_b32 m0, s45
	s_nop 0
	global_load_lds_dwordx4 v[230:231], off
	s_barrier
	s_waitcnt lgkmcnt(0)
	v_mfma_f32_16x16x32_bf16 v[64:67], v[150:153], v[166:169], v[64:67]
	v_mfma_f32_16x16x32_bf16 v[60:63], v[158:161], v[166:169], v[60:63]
	v_mfma_f32_16x16x32_bf16 v[44:47], v[150:153], v[182:185], v[44:47]
	v_mfma_f32_16x16x32_bf16 v[40:43], v[158:161], v[182:185], v[40:43]
	v_mfma_f32_16x16x32_bf16 v[28:31], v[150:153], v[190:193], v[28:31]
	v_mfma_f32_16x16x32_bf16 v[24:27], v[158:161], v[190:193], v[24:27]
	v_mfma_f32_16x16x32_bf16 v[12:15], v[150:153], v[198:201], v[12:15]
	v_mfma_f32_16x16x32_bf16 v[8:11], v[158:161], v[198:201], v[8:11]
	v_mfma_f32_16x16x32_bf16 v[64:67], v[154:157], v[170:173], v[64:67]
	v_mfma_f32_16x16x32_bf16 v[60:63], v[162:165], v[170:173], v[60:63]
	v_mfma_f32_16x16x32_bf16 v[44:47], v[154:157], v[186:189], v[44:47]
	v_mfma_f32_16x16x32_bf16 v[40:43], v[162:165], v[186:189], v[40:43]
	v_mfma_f32_16x16x32_bf16 v[28:31], v[154:157], v[194:197], v[28:31]
	v_mfma_f32_16x16x32_bf16 v[24:27], v[162:165], v[194:197], v[24:27]
	v_mfma_f32_16x16x32_bf16 v[12:15], v[154:157], v[202:205], v[12:15]
	v_mfma_f32_16x16x32_bf16 v[8:11], v[162:165], v[202:205], v[8:11]
	s_barrier
	s_add_u32 s90, s36, 0x100000
	s_addc_u32 s91, s37, 0
	s_mov_b32 m0, s77
	v_lshl_add_u64 v[150:151], s[90:91], 0, v[134:135]
	global_load_lds_dwordx4 v[150:151], off
	v_lshl_add_u64 v[150:151], s[90:91], 0, v[136:137]
	s_mov_b32 m0, s78
	s_nop 0
	global_load_lds_dwordx4 v[150:151], off
	s_waitcnt vmcnt(6)
	s_barrier
	v_mfma_f32_16x16x32_bf16 v[52:55], v[206:209], v[166:169], v[52:55]
	v_mfma_f32_16x16x32_bf16 v[48:51], v[218:221], v[166:169], v[48:51]
	v_mfma_f32_16x16x32_bf16 v[36:39], v[206:209], v[182:185], v[36:39]
	v_mfma_f32_16x16x32_bf16 v[32:35], v[218:221], v[182:185], v[32:35]
	v_mfma_f32_16x16x32_bf16 v[20:23], v[206:209], v[190:193], v[20:23]
	v_mfma_f32_16x16x32_bf16 v[16:19], v[218:221], v[190:193], v[16:19]
	v_mfma_f32_16x16x32_bf16 v[4:7], v[206:209], v[198:201], v[4:7]
	v_mfma_f32_16x16x32_bf16 v[0:3], v[218:221], v[198:201], v[0:3]
	v_mfma_f32_16x16x32_bf16 v[52:55], v[214:217], v[170:173], v[52:55]
	v_mfma_f32_16x16x32_bf16 v[48:51], v[222:225], v[170:173], v[48:51]
	v_mfma_f32_16x16x32_bf16 v[36:39], v[214:217], v[186:189], v[36:39]
	v_mfma_f32_16x16x32_bf16 v[32:35], v[222:225], v[186:189], v[32:35]
	v_mfma_f32_16x16x32_bf16 v[20:23], v[214:217], v[194:197], v[20:23]
	v_mfma_f32_16x16x32_bf16 v[16:19], v[222:225], v[194:197], v[16:19]
	v_mfma_f32_16x16x32_bf16 v[4:7], v[214:217], v[202:205], v[4:7]
	v_mfma_f32_16x16x32_bf16 v[0:3], v[222:225], v[202:205], v[0:3]
	v_add_u32_e32 v56, s79, v139
	s_barrier
	ds_read_b128 v[150:153], v56
	ds_read_b128 v[154:157], v56 offset:1024
	ds_read_b128 v[158:161], v56 offset:2048
	ds_read_b128 v[162:165], v56 offset:3072
	s_add_u32 s38, s38, 0x100000
	s_addc_u32 s39, s39, 0
	s_mov_b32 m0, s46
	v_lshl_add_u64 v[206:207], s[38:39], 0, v[134:135]
	ds_read_b128 v[166:169], v133 offset:32768
	ds_read_b128 v[170:173], v133 offset:33792
	ds_read_b128 v[182:185], v133 offset:34816
	ds_read_b128 v[186:189], v133 offset:35840
	ds_read_b128 v[190:193], v133 offset:36864
	ds_read_b128 v[194:197], v133 offset:37888
	ds_read_b128 v[198:201], v133 offset:38912
	ds_read_b128 v[202:205], v133 offset:39936
	global_load_lds_dwordx4 v[206:207], off
	v_lshl_add_u64 v[206:207], s[38:39], 0, v[136:137]
	s_mov_b32 m0, s47
	s_nop 0
	global_load_lds_dwordx4 v[206:207], off
	s_waitcnt lgkmcnt(8)
	s_barrier
	s_waitcnt lgkmcnt(0)
	v_mfma_f32_16x16x32_bf16 v[128:131], v[150:153], v[166:169], v[128:131]
	v_mfma_f32_16x16x32_bf16 v[124:127], v[158:161], v[166:169], v[124:127]
	v_mfma_f32_16x16x32_bf16 v[112:115], v[150:153], v[182:185], v[112:115]
	v_mfma_f32_16x16x32_bf16 v[108:111], v[158:161], v[182:185], v[108:111]
	v_mfma_f32_16x16x32_bf16 v[96:99], v[150:153], v[190:193], v[96:99]
	v_mfma_f32_16x16x32_bf16 v[92:95], v[158:161], v[190:193], v[92:95]
	v_mfma_f32_16x16x32_bf16 v[80:83], v[150:153], v[198:201], v[80:83]
	v_mfma_f32_16x16x32_bf16 v[76:79], v[158:161], v[198:201], v[76:79]
	v_mfma_f32_16x16x32_bf16 v[128:131], v[154:157], v[170:173], v[128:131]
	v_mfma_f32_16x16x32_bf16 v[124:127], v[162:165], v[170:173], v[124:127]
	v_mfma_f32_16x16x32_bf16 v[112:115], v[154:157], v[186:189], v[112:115]
	v_mfma_f32_16x16x32_bf16 v[108:111], v[162:165], v[186:189], v[108:111]
	v_mfma_f32_16x16x32_bf16 v[96:99], v[154:157], v[194:197], v[96:99]
	v_mfma_f32_16x16x32_bf16 v[92:95], v[162:165], v[194:197], v[92:95]
	v_mfma_f32_16x16x32_bf16 v[80:83], v[154:157], v[202:205], v[80:83]
	v_mfma_f32_16x16x32_bf16 v[76:79], v[162:165], v[202:205], v[76:79]
	s_barrier
	s_add_i32 s3, 0, 0x1c000
	s_add_i32 s38, s79, s41
	v_add_u32_e32 v56, s3, v139
	v_lshl_add_u64 v[174:175], v[174:175], 0, s[16:17]
	s_mov_b32 m0, s38
	ds_read_b128 v[206:209], v56
	ds_read_b128 v[214:217], v56 offset:1024
	ds_read_b128 v[218:221], v56 offset:2048
	ds_read_b128 v[222:225], v56 offset:3072
	global_load_lds_dwordx4 v[174:175], off
	v_lshl_add_u64 v[174:175], v[226:227], 0, s[16:17]
	s_add_i32 m0, s38, 0x2000
	s_nop 0
	global_load_lds_dwordx4 v[174:175], off
	s_barrier
	s_waitcnt lgkmcnt(0)
	v_mfma_f32_16x16x32_bf16 v[120:123], v[206:209], v[166:169], v[120:123]
	v_mfma_f32_16x16x32_bf16 v[116:119], v[218:221], v[166:169], v[116:119]
	v_mfma_f32_16x16x32_bf16 v[104:107], v[206:209], v[182:185], v[104:107]
	v_mfma_f32_16x16x32_bf16 v[100:103], v[218:221], v[182:185], v[100:103]
	v_mfma_f32_16x16x32_bf16 v[88:91], v[206:209], v[190:193], v[88:91]
	v_mfma_f32_16x16x32_bf16 v[84:87], v[218:221], v[190:193], v[84:87]
	v_mfma_f32_16x16x32_bf16 v[72:75], v[206:209], v[198:201], v[72:75]
	v_mfma_f32_16x16x32_bf16 v[68:71], v[218:221], v[198:201], v[68:71]
	v_mfma_f32_16x16x32_bf16 v[120:123], v[214:217], v[170:173], v[120:123]
	v_mfma_f32_16x16x32_bf16 v[116:119], v[222:225], v[170:173], v[116:119]
	v_mfma_f32_16x16x32_bf16 v[104:107], v[214:217], v[186:189], v[104:107]
	v_mfma_f32_16x16x32_bf16 v[100:103], v[222:225], v[186:189], v[100:103]
	v_mfma_f32_16x16x32_bf16 v[88:91], v[214:217], v[194:197], v[88:91]
	v_mfma_f32_16x16x32_bf16 v[84:87], v[222:225], v[194:197], v[84:87]
	v_mfma_f32_16x16x32_bf16 v[72:75], v[214:217], v[202:205], v[72:75]
	v_mfma_f32_16x16x32_bf16 v[68:71], v[222:225], v[202:205], v[68:71]
	s_mov_b32 m0, s67
	v_lshl_add_u64 v[174:175], v[228:229], 0, s[16:17]
	s_barrier
	ds_read_b128 v[166:169], v133 offset:49152
	ds_read_b128 v[170:173], v133 offset:50176
	ds_read_b128 v[182:185], v133 offset:51200
	ds_read_b128 v[186:189], v133 offset:52224
	ds_read_b128 v[190:193], v133 offset:53248
	ds_read_b128 v[194:197], v133 offset:54272
	ds_read_b128 v[198:201], v133 offset:55296
	ds_read_b128 v[202:205], v133 offset:56320
	global_load_lds_dwordx4 v[174:175], off
	v_lshl_add_u64 v[174:175], v[230:231], 0, s[16:17]
	s_mov_b32 m0, s68
	s_nop 0
	global_load_lds_dwordx4 v[174:175], off
	s_barrier
	s_waitcnt lgkmcnt(0)
	v_mfma_f32_16x16x32_bf16 v[64:67], v[150:153], v[166:169], v[64:67]
	v_mfma_f32_16x16x32_bf16 v[60:63], v[158:161], v[166:169], v[60:63]
	v_mfma_f32_16x16x32_bf16 v[44:47], v[150:153], v[182:185], v[44:47]
	v_mfma_f32_16x16x32_bf16 v[40:43], v[158:161], v[182:185], v[40:43]
	v_mfma_f32_16x16x32_bf16 v[28:31], v[150:153], v[190:193], v[28:31]
	v_mfma_f32_16x16x32_bf16 v[24:27], v[158:161], v[190:193], v[24:27]
	v_mfma_f32_16x16x32_bf16 v[12:15], v[150:153], v[198:201], v[12:15]
	v_mfma_f32_16x16x32_bf16 v[8:11], v[158:161], v[198:201], v[8:11]
	v_mfma_f32_16x16x32_bf16 v[64:67], v[154:157], v[170:173], v[64:67]
	v_mfma_f32_16x16x32_bf16 v[60:63], v[162:165], v[170:173], v[60:63]
	v_mfma_f32_16x16x32_bf16 v[44:47], v[154:157], v[186:189], v[44:47]
	v_mfma_f32_16x16x32_bf16 v[40:43], v[162:165], v[186:189], v[40:43]
	v_mfma_f32_16x16x32_bf16 v[28:31], v[154:157], v[194:197], v[28:31]
	v_mfma_f32_16x16x32_bf16 v[24:27], v[162:165], v[194:197], v[24:27]
	v_mfma_f32_16x16x32_bf16 v[12:15], v[154:157], v[202:205], v[12:15]
	v_mfma_f32_16x16x32_bf16 v[8:11], v[162:165], v[202:205], v[8:11]
	s_barrier
	s_add_u32 s36, s36, 0x100080
	s_addc_u32 s37, s37, 0
	s_add_i32 s3, s3, s41
	v_lshl_add_u64 v[150:151], s[36:37], 0, v[134:135]
	s_mov_b32 m0, s3
	s_nop 0
	global_load_lds_dwordx4 v[150:151], off
	v_lshl_add_u64 v[150:151], s[36:37], 0, v[136:137]
	s_add_i32 m0, s3, 0x2000
	s_nop 0
	global_load_lds_dwordx4 v[150:151], off
	s_waitcnt vmcnt(6)
	s_barrier
	v_mfma_f32_16x16x32_bf16 v[52:55], v[206:209], v[166:169], v[52:55]
	v_mfma_f32_16x16x32_bf16 v[48:51], v[218:221], v[166:169], v[48:51]
	v_mfma_f32_16x16x32_bf16 v[36:39], v[206:209], v[182:185], v[36:39]
	v_mfma_f32_16x16x32_bf16 v[32:35], v[218:221], v[182:185], v[32:35]
	v_mfma_f32_16x16x32_bf16 v[20:23], v[206:209], v[190:193], v[20:23]
	v_mfma_f32_16x16x32_bf16 v[16:19], v[218:221], v[190:193], v[16:19]
	v_mfma_f32_16x16x32_bf16 v[4:7], v[206:209], v[198:201], v[4:7]
	v_mfma_f32_16x16x32_bf16 v[0:3], v[218:221], v[198:201], v[0:3]
	v_mfma_f32_16x16x32_bf16 v[52:55], v[214:217], v[170:173], v[52:55]
	v_mfma_f32_16x16x32_bf16 v[48:51], v[222:225], v[170:173], v[48:51]
	v_mfma_f32_16x16x32_bf16 v[36:39], v[214:217], v[186:189], v[36:39]
	v_mfma_f32_16x16x32_bf16 v[32:35], v[222:225], v[186:189], v[32:35]
	v_mfma_f32_16x16x32_bf16 v[20:23], v[214:217], v[194:197], v[20:23]
	v_mfma_f32_16x16x32_bf16 v[16:19], v[222:225], v[194:197], v[16:19]
	v_mfma_f32_16x16x32_bf16 v[4:7], v[214:217], v[202:205], v[4:7]
	v_mfma_f32_16x16x32_bf16 v[0:3], v[222:225], v[202:205], v[0:3]
	s_add_u32 s34, s34, 0x100
	s_addc_u32 s35, s35, 0
	s_cmp_ge_u32 s89, s49
	s_barrier
	s_cbranch_scc0 .LBB0_640
	s_add_u32 s34, s83, 0xffffff00
	s_addc_u32 s35, s84, -1
	s_and_b64 vcc, exec, s[28:29]
	s_cbranch_vccnz .LBB0_638
	s_mov_b64 s[8:9], s[34:35]
	s_andn2_b64 vcc, exec, s[20:21]
	s_cbranch_vccnz .LBB0_639
